# HGRN gate block: packed f32 mul/add/fma for sigmoid prep (pk_mul + min instead of max + mul; pk_add; pk_fma), 18 fewer VALU per chunk, bit-identical
# baseline (speedup 1.0000x reference)
; __device__ __forceinline__ void hgrn_chain(const Params& p, LAS unsigned char* lds, int layer, int chain, int dvh) {
;     ...
;         if (c + 1 < SEQ / 64) { HG_A1(cur ^ 1); if (c + 2 < SEQ / 64) HG_LOAD(c + 2); }
.LBB0_426:
	s_xor_b32 s57, s0, 1
	s_cmpk_lg_i32 s72, 0xf840
	v_cvt_pk_bf16_f32 v34, v35, v36
	v_add_u32_e32 v36, s78, v126
	s_cselect_b64 s[70:71], -1, 0
	s_cmpk_eq_i32 s72, 0xf840
	v_cvt_pk_bf16_f32 v35, v37, v85
	ds_write_b64 v36, v[34:35]
	s_cbranch_scc1 .LBB0_442
	s_waitcnt vmcnt(0)
	s_mov_b32 s0, 0xbfb8aa3b
	s_mov_b32 s1, 0xbfb8aa3b
	s_mov_b32 s96, 1.0
	s_mov_b32 s97, 1.0
	v_lshlrev_b32_e32 v63, 16, v92
	v_lshlrev_b32_e32 v62, 16, v93
	v_lshlrev_b32_e32 v67, 16, v95
	v_lshlrev_b32_e32 v66, 16, v96
	v_lshlrev_b32_e32 v71, 16, v97
	v_lshlrev_b32_e32 v70, 16, v98
	v_lshlrev_b32_e32 v75, 16, v99
	v_lshlrev_b32_e32 v74, 16, v100
	v_lshlrev_b32_e32 v79, 16, v101
	v_lshlrev_b32_e32 v78, 16, v102
	v_lshlrev_b32_e32 v83, 16, v103
	v_lshlrev_b32_e32 v82, 16, v104
	v_lshlrev_b32_e32 v45, 16, v105
	v_lshlrev_b32_e32 v44, 16, v89
	v_lshlrev_b32_e32 v7, 16, v90
	v_lshlrev_b32_e32 v6, 16, v91
	v_pk_mul_f32 v[62:63], v[62:63], s[0:1]
	v_pk_mul_f32 v[66:67], v[66:67], s[0:1]
	v_pk_mul_f32 v[70:71], v[70:71], s[0:1]
	v_pk_mul_f32 v[74:75], v[74:75], s[0:1]
	v_pk_mul_f32 v[78:79], v[78:79], s[0:1]
	v_pk_mul_f32 v[82:83], v[82:83], s[0:1]
	v_pk_mul_f32 v[44:45], v[44:45], s[0:1]
	v_pk_mul_f32 v[6:7], v[6:7], s[0:1]
	v_min_f32_e32 v62, 0x42ad1f97, v62
	v_min_f32_e32 v63, 0x42ad1f97, v63
	v_min_f32_e32 v66, 0x42ad1f97, v66
	v_min_f32_e32 v67, 0x42ad1f97, v67
	v_min_f32_e32 v70, 0x42ad1f97, v70
	v_min_f32_e32 v71, 0x42ad1f97, v71
	v_min_f32_e32 v74, 0x42ad1f97, v74
	v_min_f32_e32 v75, 0x42ad1f97, v75
	v_min_f32_e32 v78, 0x42ad1f97, v78
	v_min_f32_e32 v79, 0x42ad1f97, v79
	v_min_f32_e32 v82, 0x42ad1f97, v82
	v_min_f32_e32 v83, 0x42ad1f97, v83
	v_min_f32_e32 v44, 0x42ad1f97, v44
	v_min_f32_e32 v45, 0x42ad1f97, v45
	v_min_f32_e32 v6, 0x42ad1f97, v6
	v_min_f32_e32 v7, 0x42ad1f97, v7
	v_exp_f32_e32 v62, v62
	v_exp_f32_e32 v63, v63
	v_exp_f32_e32 v66, v66
	v_exp_f32_e32 v67, v67
	v_exp_f32_e32 v70, v70
	v_exp_f32_e32 v71, v71
	v_exp_f32_e32 v74, v74
	v_exp_f32_e32 v75, v75
	v_exp_f32_e32 v78, v78
	v_exp_f32_e32 v79, v79
	v_exp_f32_e32 v82, v82
	v_exp_f32_e32 v83, v83
	v_exp_f32_e32 v44, v44
	v_exp_f32_e32 v45, v45
	v_exp_f32_e32 v6, v6
	v_exp_f32_e32 v7, v7
	v_pk_add_f32 v[64:65], v[62:63], s[96:97]
	v_pk_add_f32 v[68:69], v[66:67], s[96:97]
	v_pk_add_f32 v[72:73], v[70:71], s[96:97]
	v_pk_add_f32 v[76:77], v[74:75], s[96:97]
	v_pk_add_f32 v[80:81], v[78:79], s[96:97]
	v_pk_add_f32 v[84:85], v[82:83], s[96:97]
	v_pk_add_f32 v[34:35], v[44:45], s[96:97]
	v_pk_add_f32 v[8:9], v[6:7], s[96:97]
	v_rcp_f32_e32 v9, v9
	v_rcp_f32_e32 v8, v8
	v_rcp_f32_e32 v43, v35
	v_rcp_f32_e32 v35, v34
	v_rcp_f32_e32 v64, v64
	v_rcp_f32_e32 v65, v65
	v_rcp_f32_e32 v68, v68
	v_rcp_f32_e32 v69, v69
	v_rcp_f32_e32 v72, v72
	v_rcp_f32_e32 v73, v73
	v_rcp_f32_e32 v76, v76
	v_rcp_f32_e32 v77, v77
	v_rcp_f32_e32 v80, v80
	v_rcp_f32_e32 v81, v81
	v_rcp_f32_e32 v84, v84
	v_rcp_f32_e32 v85, v85
	v_mul_f32_e32 v37, v40, v44
	v_mul_f32_e32 v44, v40, v9
	v_pk_add_f32 v[46:47], v[38:39], v[44:45]
	v_pk_mul_f32 v[44:45], v[38:39], v[44:45]
	v_fma_f32 v42, v40, v35, v38
	v_mov_b32_e32 v47, v45
	v_pk_fma_f32 v[56:57], v[40:41], v[64:65], v[38:39] op_sel:[0,1,0] op_sel_hi:[0,0,0]
	v_pk_mul_f32 v[44:45], v[46:47], v[42:43]
	v_fma_f32 v36, v40, v8, v38
	v_pk_fma_f32 v[58:59], v[40:41], v[68:69], v[38:39] op_sel:[0,1,0] op_sel_hi:[0,0,0]
	v_mov_b32_e32 v34, v44
	v_pk_fma_f32 v[60:61], v[40:41], v[72:73], v[38:39] op_sel:[0,1,0] op_sel_hi:[0,0,0]
	v_pk_mul_f32 v[46:47], v[34:35], v[36:37]
	v_pk_fma_f32 v[112:113], v[40:41], v[76:77], v[38:39] op_sel:[0,1,0] op_sel_hi:[0,0,0]
	v_pk_fma_f32 v[114:115], v[40:41], v[80:81], v[38:39] op_sel:[0,1,0] op_sel_hi:[0,0,0]
	v_pk_fma_f32 v[116:117], v[40:41], v[84:85], v[38:39] op_sel:[0,1,0] op_sel_hi:[0,0,0]
	v_fma_f32 v118, v40, v43, v38
	v_mul_f32_e32 v106, v46, v56
	v_mul_f32_e32 v107, v106, v57
	v_mul_f32_e32 v108, v107, v58
	v_mul_f32_e32 v109, v108, v59
	v_mul_f32_e32 v110, v109, v60
	v_mul_f32_e32 v111, v110, v61
	v_mul_f32_e32 v112, v111, v112
	v_mul_f32_e32 v113, v112, v113
	v_mul_f32_e32 v114, v113, v114
	v_mul_f32_e32 v115, v114, v115
	v_mul_f32_e32 v116, v115, v116
	v_mul_f32_e32 v117, v116, v117
	v_mul_f32_e32 v118, v117, v118
	v_lshl_add_u32 v34, s57, 11, v94
	ds_write_b32 v34, v118
	s_waitcnt vmcnt(0)
	s_cmp_gt_u32 s56, 29
	v_perm_b32 v152, v194, v195, s87
	v_perm_b32 v151, v196, v197, s87
	v_perm_b32 v150, v198, v199, s87
	v_perm_b32 v149, v200, v201, s87
	v_perm_b32 v148, v202, v203, s87
	v_perm_b32 v147, v204, v205, s87
	v_perm_b32 v146, v206, v207, s87
	v_perm_b32 v145, v208, v209, s87
	v_mov_b64_e32 v[2:3], v[210:211]
	v_mov_b64_e32 v[4:5], v[212:213]
	s_cbranch_scc1 .LBB0_441
	v_cndmask_b32_e64 v34, 0, 1, s[8:9]
	s_mov_b64 s[96:97], -1
	v_cmp_ne_u32_e64 s[0:1], 1, v34
	s_andn2_b64 vcc, exec, s[8:9]
	v_add_u32_e32 v34, s72, v138
	s_cbranch_vccnz .LBB0_432
	v_add_u32_e32 v36, s72, v138
	s_add_i32 s59, s56, 2
	v_lshl_add_u32 v35, s59, 6, v87
	s_cbranch_execz .LBB0_433
